# G2 split-K sample-row GEMM also staged through LDS-DMA (same scheme as G4)
# speedup vs baseline: 1.0060x; 1.0030x over previous
.LBB0_789:
	s_movk_i32 s22, 0x1400
	s_movk_i32 s23, 0x800
	s_and_b32 s2, s13, 0x70
	v_or_b32_e32 v5, s2, v12
	v_mul_u32_u24_e32 v6, 0xa00, v5
	s_and_b32 s6, s14, 0xffffffe0
	v_lshlrev_b32_e32 v194, 1, v6
	v_or_b32_e32 v6, s6, v12
	v_ashrrev_i32_e32 v7, 31, v6
	v_lshlrev_b64 v[8:9], 11, v[6:7]
	v_lshl_add_u64 v[34:35], v[2:3], 0, v[8:9]
	v_or_b32_e32 v14, 16, v6
	v_ashrrev_i32_e32 v15, 31, v14
	v_lshl_add_u64 v[10:11], v[0:1], 0, v[194:195]
	v_lshlrev_b64 v[14:15], 11, v[14:15]
	v_lshl_add_u64 v[36:37], v[2:3], 0, v[14:15]
	s_andn2_b64 vcc, exec, s[4:5]
	v_add_u32_e32 v10, s12, v13
	v_mbcnt_lo_u32_b32 v40, -1, 0
	v_mbcnt_hi_u32_b32 v40, -1, v40
	v_lshrrev_b32_e32 v41, 2, v40
	v_lshrrev_b32_e32 v42, 4, v40
	v_and_b32_e32 v43, 3, v40
	v_xor_b32_e32 v43, v43, v42
	v_sub_u32_e32 v43, v43, v42
	v_lshlrev_b32_e32 v43, 4, v43
	s_and_b32 s56, s13, 0x70
	v_add_u32_e32 v44, s56, v41
	v_mad_u32_u24 v44, v44, s22, v43
	v_ashrrev_i32_e32 v45, 31, v44
	v_lshl_add_u64 v[44:45], v[0:1], 0, v[44:45]
	v_add_u32_e32 v46, s6, v41
	v_mad_u32_u24 v46, v46, s23, v43
	v_ashrrev_i32_e32 v47, 31, v46
	v_lshl_add_u64 v[46:47], v[2:3], 0, v[46:47]
	s_lshl_b32 s58, s23, 4
	s_mov_b32 s59, 0
	v_lshl_add_u64 v[48:49], v[46:47], 0, s[58:59]
	v_lshrrev_b32_e32 v50, 2, v12
	v_xor_b32_e32 v50, v50, v42
	v_lshlrev_b32_e32 v50, 4, v50
	v_lshl_or_b32 v50, v12, 6, v50
	s_mul_i32 s57, s89, 0x3000
	s_add_i32 s57, s57, 0x4000
	v_add_u32_e32 v50, s57, v50
	s_add_i32 m0, s57, 0
	s_nop 0
	global_load_lds_dwordx4 v[44:45], off
	s_add_i32 m0, s57, 1024
	s_nop 0
	global_load_lds_dwordx4 v[46:47], off
	s_add_i32 m0, s57, 2048
	s_nop 0
	global_load_lds_dwordx4 v[48:49], off
	s_add_i32 m0, s57, 3008
	s_nop 0
	global_load_lds_dwordx4 v[44:45], off offset:64
	s_add_i32 m0, s57, 4032
	s_nop 0
	global_load_lds_dwordx4 v[46:47], off offset:64
	s_add_i32 m0, s57, 5056
	s_nop 0
	global_load_lds_dwordx4 v[48:49], off offset:64
	s_add_i32 m0, s57, 6016
	s_nop 0
	global_load_lds_dwordx4 v[44:45], off offset:128
	s_add_i32 m0, s57, 7040
	s_nop 0
	global_load_lds_dwordx4 v[46:47], off offset:128
	s_add_i32 m0, s57, 8064
	s_nop 0
	global_load_lds_dwordx4 v[48:49], off offset:128
	s_add_i32 m0, s57, 9024
	s_nop 0
	global_load_lds_dwordx4 v[44:45], off offset:192
	s_add_i32 m0, s57, 10048
	s_nop 0
	global_load_lds_dwordx4 v[46:47], off offset:192
	s_add_i32 m0, s57, 11072
	s_nop 0
	global_load_lds_dwordx4 v[48:49], off offset:192
	s_waitcnt vmcnt(9)
	ds_read_b128 v[52:55], v50 offset:0
	ds_read_b128 v[56:59], v50 offset:1024
	ds_read_b128 v[60:63], v50 offset:2048
	s_waitcnt lgkmcnt(0)
	v_mfma_f32_16x16x32_bf16 v[6:9], v[56:59], v[52:55], 0
	v_mfma_f32_16x16x32_bf16 v[14:17], v[60:63], v[52:55], 0
	s_waitcnt vmcnt(6)
	ds_read_b128 v[64:67], v50 offset:3072
	ds_read_b128 v[68:71], v50 offset:4096
	ds_read_b128 v[72:75], v50 offset:5120
	s_waitcnt lgkmcnt(0)
	v_mfma_f32_16x16x32_bf16 v[6:9], v[68:71], v[64:67], v[6:9]
	v_mfma_f32_16x16x32_bf16 v[14:17], v[72:75], v[64:67], v[14:17]
	s_waitcnt vmcnt(3)
	ds_read_b128 v[52:55], v50 offset:6144
	ds_read_b128 v[56:59], v50 offset:7168
	ds_read_b128 v[60:63], v50 offset:8192
	s_waitcnt lgkmcnt(0)
	v_mfma_f32_16x16x32_bf16 v[6:9], v[56:59], v[52:55], v[6:9]
	v_mfma_f32_16x16x32_bf16 v[14:17], v[60:63], v[52:55], v[14:17]
	s_waitcnt vmcnt(0)
	ds_read_b128 v[64:67], v50 offset:9216
	ds_read_b128 v[68:71], v50 offset:10240
	ds_read_b128 v[72:75], v50 offset:11264
	s_waitcnt lgkmcnt(0)
	v_mfma_f32_16x16x32_bf16 v[6:9], v[68:71], v[64:67], v[6:9]
	v_mfma_f32_16x16x32_bf16 v[14:17], v[72:75], v[64:67], v[14:17]
	s_nop 6
	ds_write_b128 v10, v[6:9]
	ds_write_b128 v10, v[14:17] offset:16
	s_waitcnt lgkmcnt(0)
	s_barrier
	s_cbranch_vccnz .LBB0_788
	v_add_u32_e32 v24, 0, v13
	ds_read_b128 v[6:9], v24
	ds_read_b128 v[14:17], v24 offset:16
	s_ashr_i32 s7, s6, 31
	s_waitcnt lgkmcnt(1)
	v_pk_add_f32 v[10:11], v[8:9], 0 op_sel_hi:[1,0]
	v_pk_add_f32 v[18:19], v[6:7], 0 op_sel_hi:[1,0]
	ds_read_b128 v[6:9], v24 offset:2048
	s_waitcnt lgkmcnt(1)
	v_pk_add_f32 v[16:17], v[16:17], 0 op_sel_hi:[1,0]
	v_pk_add_f32 v[14:15], v[14:15], 0 op_sel_hi:[1,0]
	s_waitcnt lgkmcnt(0)
	v_pk_add_f32 v[10:11], v[10:11], v[8:9]
	v_pk_add_f32 v[18:19], v[18:19], v[6:7]
	ds_read_b128 v[6:9], v24 offset:2064
	s_waitcnt lgkmcnt(0)
	v_pk_add_f32 v[16:17], v[16:17], v[8:9]
	v_pk_add_f32 v[14:15], v[14:15], v[6:7]
	ds_read_b128 v[6:9], v24 offset:4096
	s_waitcnt lgkmcnt(0)
	v_pk_add_f32 v[10:11], v[10:11], v[8:9]
	v_pk_add_f32 v[18:19], v[18:19], v[6:7]
	ds_read_b128 v[6:9], v24 offset:4112
	s_waitcnt lgkmcnt(0)
	v_pk_add_f32 v[16:17], v[16:17], v[8:9]
	v_pk_add_f32 v[14:15], v[14:15], v[6:7]
	ds_read_b128 v[6:9], v24 offset:6144
	s_waitcnt lgkmcnt(0)
	v_pk_add_f32 v[10:11], v[10:11], v[8:9]
	v_pk_add_f32 v[18:19], v[18:19], v[6:7]
	ds_read_b128 v[6:9], v24 offset:6160
	s_waitcnt lgkmcnt(0)
	v_pk_add_f32 v[16:17], v[16:17], v[8:9]
	v_pk_add_f32 v[14:15], v[14:15], v[6:7]
	ds_read_b128 v[6:9], v24 offset:8192
	s_waitcnt lgkmcnt(0)
	v_pk_add_f32 v[10:11], v[10:11], v[8:9]
	v_pk_add_f32 v[18:19], v[18:19], v[6:7]
	ds_read_b128 v[6:9], v24 offset:8208
	s_waitcnt lgkmcnt(0)
	v_pk_add_f32 v[16:17], v[16:17], v[8:9]
	v_pk_add_f32 v[14:15], v[14:15], v[6:7]
	ds_read_b128 v[6:9], v24 offset:10240
	s_waitcnt lgkmcnt(0)
	v_pk_add_f32 v[10:11], v[10:11], v[8:9]
	v_pk_add_f32 v[18:19], v[18:19], v[6:7]
	ds_read_b128 v[6:9], v24 offset:10256
	s_waitcnt lgkmcnt(0)
	v_pk_add_f32 v[16:17], v[16:17], v[8:9]
	v_pk_add_f32 v[14:15], v[14:15], v[6:7]
	ds_read_b128 v[6:9], v24 offset:12288
	s_waitcnt lgkmcnt(0)
	v_pk_add_f32 v[10:11], v[10:11], v[8:9]
	v_pk_add_f32 v[18:19], v[18:19], v[6:7]
	ds_read_b128 v[6:9], v24 offset:12304
	s_waitcnt lgkmcnt(0)
	v_pk_add_f32 v[20:21], v[16:17], v[8:9]
	v_pk_add_f32 v[22:23], v[14:15], v[6:7]
	ds_read_b128 v[6:9], v24 offset:14336
	ds_read_b128 v[14:17], v24 offset:14352
	s_waitcnt lgkmcnt(1)
	v_pk_add_f32 v[8:9], v[10:11], v[8:9]
	s_waitcnt lgkmcnt(0)
	v_pk_add_f32 v[10:11], v[22:23], v[14:15]
	v_or_b32_e32 v14, 0x4000, v5
	v_lshlrev_b32_e32 v194, 11, v14
	v_pk_add_f32 v[18:19], v[18:19], v[6:7]
	v_pk_add_f32 v[6:7], v[20:21], v[16:17]
	v_lshl_add_u64 v[16:17], s[0:1], 0, v[194:195]
	v_lshl_add_u64 v[16:17], s[6:7], 1, v[16:17]
	v_mov_b32_e32 v5, v195
	v_lshl_add_u64 v[16:17], v[16:17], 0, v[4:5]
	global_load_dwordx2 v[20:21], v[16:17], off
	global_load_dwordx2 v[22:23], v[16:17], off offset:32
	s_waitcnt vmcnt(0) lgkmcnt(0)
	v_lshlrev_b32_e32 v24, 16, v20
	v_and_b32_e32 v25, 0xffff0000, v20
	v_lshlrev_b32_e32 v20, 16, v21
	v_and_b32_e32 v21, 0xffff0000, v21
	v_pk_add_f32 v[18:19], v[18:19], v[24:25]
	v_pk_add_f32 v[8:9], v[8:9], v[20:21]
	v_cvt_pk_bf16_f32 v18, v18, v19
	v_cvt_pk_bf16_f32 v19, v8, v9
	v_lshlrev_b32_e32 v8, 16, v22
	v_and_b32_e32 v9, 0xffff0000, v22
	v_pk_add_f32 v[8:9], v[10:11], v[8:9]
	v_lshlrev_b32_e32 v10, 16, v23
	v_and_b32_e32 v11, 0xffff0000, v23
	v_pk_add_f32 v[6:7], v[6:7], v[10:11]
	v_cvt_pk_bf16_f32 v8, v8, v9
	v_cvt_pk_bf16_f32 v9, v6, v7
	v_and_b32_e32 v6, 0xffff0000, v18
	v_lshlrev_b32_e32 v5, 16, v18
	v_and_b32_e32 v10, 0xffff0000, v19
	v_mul_f32_e32 v6, v6, v6
	v_lshlrev_b32_e32 v7, 16, v19
	v_fmac_f32_e32 v6, v5, v5
	v_mul_f32_e32 v5, v10, v10
	global_store_dwordx2 v[16:17], v[18:19], off
	global_store_dwordx2 v[16:17], v[8:9], off offset:32
	v_lshlrev_b32_e32 v11, 16, v8
	v_and_b32_e32 v8, 0xffff0000, v8
	v_fmac_f32_e32 v5, v7, v7
	v_add_f32_e32 v5, v6, v5
	v_mul_f32_e32 v6, v8, v8
	v_lshlrev_b32_e32 v15, 16, v9
	v_and_b32_e32 v9, 0xffff0000, v9
	v_fmac_f32_e32 v6, v11, v11
	v_add_f32_e32 v5, v5, v6
	v_mul_f32_e32 v6, v9, v9
	v_fmac_f32_e32 v6, v15, v15
	v_and_b32_e32 v7, 64, v243
	v_add_f32_e32 v5, v6, v5
	v_xor_b32_e32 v6, 16, v243
	v_add_u32_e32 v7, 64, v7
	v_cmp_lt_i32_e32 vcc, v6, v7
	s_nop 1
	v_cndmask_b32_e32 v6, v243, v6, vcc
	v_lshlrev_b32_e32 v6, 2, v6
	ds_bpermute_b32 v6, v6, v5
	s_waitcnt lgkmcnt(0)
	v_add_f32_e32 v5, v5, v6
	v_xor_b32_e32 v6, 32, v243
	v_cmp_lt_i32_e32 vcc, v6, v7
	s_nop 1
	v_cndmask_b32_e32 v6, v243, v6, vcc
	v_lshlrev_b32_e32 v6, 2, v6
	ds_bpermute_b32 v6, v6, v5
	s_and_saveexec_b64 s[2:3], s[8:9]
	s_cbranch_execz .LBB0_787
	s_waitcnt lgkmcnt(0)
	v_add_f32_e32 v5, v5, v6
	s_mov_b32 s6, 0x4b800000
	v_fma_f32 v5, v5, s6, 0.5
	v_trunc_f32_e32 v5, v5
	v_mul_f32_e32 v6, 0x2f800000, v5
	v_floor_f32_e32 v7, v6
	v_fmac_f32_e32 v5, 0xcf800000, v7
	v_cvt_u32_f32_e32 v6, v5
	v_cvt_u32_f32_e32 v7, v7
	v_lshlrev_b32_e32 v194, 3, v14
	v_lshl_add_u64 v[8:9], s[10:11], 0, v[194:195]
	global_atomic_add_x2 v[8:9], v[6:7], off
	s_branch .LBB0_787
